# out-projection epilogue: the eight row partials fetched in one round trip; acquire fences after the two in-phase row-statistics exchanges dropped (partials travel sc1 store to sc1 load)
# speedup vs baseline: 1.0402x; 1.0073x over previous
.LBB0_1292:
	global_load_dword v218, v209, s[38:39] sc1
	s_mov_b64 s[30:31], -1
	s_waitcnt vmcnt(0)
	v_cmp_lt_u32_e32 vcc, 7, v218
	s_cbranch_vccnz .LBB0_1291
	s_sleep 2
	global_load_dword v218, v209, s[38:39] sc1
	s_waitcnt vmcnt(0)
	v_cmp_gt_u32_e32 vcc, 8, v218
	s_cbranch_vccz .LBB0_1291
	s_sleep 2
	global_load_dword v218, v209, s[38:39] sc1
	s_waitcnt vmcnt(0)
	v_cmp_gt_u32_e32 vcc, 8, v218
	s_cbranch_vccz .LBB0_1291
	s_sleep 2
	global_load_dword v218, v209, s[38:39] sc1
	s_waitcnt vmcnt(0)
	v_cmp_gt_u32_e32 vcc, 8, v218
	s_cbranch_vccz .LBB0_1291
	s_sleep 2
	global_load_dword v218, v209, s[38:39] sc1
	s_waitcnt vmcnt(0)
	v_cmp_gt_u32_e32 vcc, 8, v218
	s_cbranch_vccz .LBB0_1291
	s_add_i32 s40, s40, -5
	s_cmp_eq_u32 s40, 0
	s_cselect_b64 s[30:31], -1, 0
	s_sleep 2
	s_branch .LBB0_1291
.LBB0_1298:
	s_waitcnt vmcnt(0)
.LBB0_1299:
	s_or_b64 exec, exec, s[22:23]
	s_barrier
	s_and_saveexec_b64 s[22:23], s[6:7]
	s_cbranch_execz .LBB0_1301
	s_waitcnt lgkmcnt(0)
	v_lshlrev_b64 v[218:219], 5, v[214:215]
	v_lshl_add_u64 v[218:219], s[14:15], 0, v[218:219]
	global_load_dwordx4 v[220:223], v[218:219], off sc1
	global_load_dwordx2 v[224:225], v[218:219], off offset:16 sc1
	global_load_dwordx2 v[218:219], v[218:219], off offset:24 sc1
	s_waitcnt vmcnt(2)
	v_add_f32_e32 v220, 0, v220
	v_add_f32_e32 v220, v220, v221
	v_add_f32_e32 v220, v220, v222
	v_add_f32_e32 v220, v220, v223
	s_waitcnt vmcnt(1)
	v_add_f32_e32 v220, v220, v224
	v_add_f32_e32 v220, v220, v225
	s_waitcnt vmcnt(0)
	v_add_f32_e32 v220, v220, v218
	v_add_f32_e32 v218, v220, v219
	v_fmamk_f32 v218, v218, 0x3a000000, v231
	v_cmp_gt_f32_e32 vcc, s37, v218
	v_mul_f32_e32 v219, 0x4b800000, v218
	s_nop 0
	v_cndmask_b32_e32 v218, v218, v219, vcc
	v_rsq_f32_e32 v218, v218
	s_nop 0
	v_mul_f32_e32 v219, 0x45800000, v218
	v_cndmask_b32_e32 v218, v218, v219, vcc
	v_lshl_add_u32 v219, v246, 2, 0
	ds_write_b32 v219, v218 offset:4096

.LBB0_1331:
	s_waitcnt lgkmcnt(0)
	s_waitcnt vmcnt(0)
.LBB0_1332:
	s_or_b64 exec, exec, s[22:23]
	s_barrier
	s_and_saveexec_b64 s[8:9], s[6:7]
	s_cbranch_execz .LBB0_1334
	s_waitcnt lgkmcnt(0)
	v_lshlrev_b64 v[128:129], 5, v[214:215]
	v_lshl_add_u64 v[128:129], s[14:15], 0, v[128:129]
	global_load_dwordx4 v[132:135], v[128:129], off sc1
	global_load_dwordx4 v[136:139], v[128:129], off offset:16 sc1
	s_waitcnt vmcnt(1)
	v_add_f32_e32 v130, 0, v132
	v_add_f32_e32 v130, v130, v133
	v_add_f32_e32 v130, v130, v134
	v_add_f32_e32 v130, v130, v135
	s_waitcnt vmcnt(0)
	v_add_f32_e32 v130, v130, v136
	v_add_f32_e32 v130, v130, v137
	v_add_f32_e32 v130, v130, v138
	v_add_f32_e32 v128, v130, v139
	v_fmamk_f32 v128, v128, 0x3a000000, v231
	v_cmp_gt_f32_e32 vcc, s37, v128
	v_mul_f32_e32 v129, 0x4b800000, v128
	s_nop 0
	v_cndmask_b32_e32 v128, v128, v129, vcc
	v_rsq_f32_e32 v128, v128
	s_nop 0
	v_mul_f32_e32 v129, 0x45800000, v128
	v_cndmask_b32_e32 v128, v128, v129, vcc
	v_lshl_add_u32 v129, v246, 2, 0
	ds_write_b32 v129, v128 offset:4096
